# GEMM units: redundant second accumulator zeroing moved off the hot path
# baseline (speedup 1.0000x reference)
; template <class Epi, class Sched, bool ALIGN_EPI = false, bool SP2 = false>
; __device__ __forceinline__ void gemm_phase(PG8_LAS unsigned char* lds, const Gemm g, const Sched& S, const Epi& E) {
;     ...
;         for (int t = 0; t < nt; t += 2) {
;             const bool last = (t == nt - 2);
;             const char* a1 = cA + (size_t)(t + 1) * kstep;
;             const char* a2 = last ? nA : cA + (size_t)(t + 2) * kstep; const char* b2 = last ? nB : cB + (size_t)(t + 2) * kstep;
;             const char* a3 = a2 + kstep; const char* b3 = b2 + kstep;
;     ...
; #pragma unroll
;         for (int a = 0; a < 2; ++a)
; #pragma unroll
;             for (int b = 0; b < 2; ++b)
; #pragma unroll
;                 for (int m = 0; m < 4; ++m)
; #pragma unroll
;                     for (int n = 0; n < 2; ++n) acc[a][b][m][n] = (f32x4){0.f, 0.f, 0.f, 0.f};
;         cur = nxt; cA = nA; cB = nB; ++ui;
.LBB0_339:
	s_andn2_b64 vcc, exec, s[52:53]
	s_cbranch_vccz .Lz_enter_339
	v_mov_b32_e32 v137, 0
	v_mov_b32_e32 v136, v137
	v_mov_b32_e32 v135, v137
	v_mov_b32_e32 v134, v137
	v_mov_b32_e32 v133, v137
	v_mov_b32_e32 v132, v137
	v_mov_b32_e32 v131, v137
	v_mov_b32_e32 v130, v137
	v_mov_b32_e32 v129, v137
	v_mov_b32_e32 v128, v137
	v_mov_b32_e32 v127, v137
	v_mov_b32_e32 v126, v137
	v_mov_b32_e32 v125, v137
	v_mov_b32_e32 v124, v137
	v_mov_b32_e32 v123, v137
	v_mov_b32_e32 v122, v137
	v_mov_b32_e32 v121, v137
	v_mov_b32_e32 v120, v137
	v_mov_b32_e32 v119, v137
	v_mov_b32_e32 v118, v137
	v_mov_b32_e32 v117, v137
	v_mov_b32_e32 v116, v137
	v_mov_b32_e32 v115, v137
	v_mov_b32_e32 v114, v137
	v_mov_b32_e32 v113, v137
	v_mov_b32_e32 v112, v137
	v_mov_b32_e32 v111, v137
	v_mov_b32_e32 v110, v137
	v_mov_b32_e32 v109, v137
	v_mov_b32_e32 v108, v137
	v_mov_b32_e32 v107, v137
	v_mov_b32_e32 v106, v137
	v_mov_b32_e32 v65, v137
	v_mov_b32_e32 v64, v137
	v_mov_b32_e32 v63, v137
	v_mov_b32_e32 v62, v137
	v_mov_b32_e32 v61, v137
	v_mov_b32_e32 v60, v137
	v_mov_b32_e32 v59, v137
	v_mov_b32_e32 v58, v137
	v_mov_b32_e32 v57, v137
	v_mov_b32_e32 v56, v137
	v_mov_b32_e32 v55, v137
	v_mov_b32_e32 v54, v137
	v_mov_b32_e32 v53, v137
	v_mov_b32_e32 v52, v137
	v_mov_b32_e32 v51, v137
	v_mov_b32_e32 v50, v137
	v_mov_b32_e32 v49, v137
	v_mov_b32_e32 v48, v137
	v_mov_b32_e32 v47, v137
	v_mov_b32_e32 v46, v137
	v_mov_b32_e32 v45, v137
	v_mov_b32_e32 v44, v137
	v_mov_b32_e32 v43, v137
	v_mov_b32_e32 v42, v137
	v_mov_b32_e32 v41, v137
	v_mov_b32_e32 v40, v137
	v_mov_b32_e32 v39, v137
	v_mov_b32_e32 v38, v137
	v_mov_b32_e32 v37, v137
	v_mov_b32_e32 v36, v137
	v_mov_b32_e32 v35, v137
	v_mov_b32_e32 v34, v137
	v_mov_b32_e32 v105, v137
	v_mov_b32_e32 v104, v137
	v_mov_b32_e32 v103, v137
	v_mov_b32_e32 v102, v137
	v_mov_b32_e32 v101, v137
	v_mov_b32_e32 v100, v137
	v_mov_b32_e32 v99, v137
	v_mov_b32_e32 v98, v137
	v_mov_b32_e32 v97, v137
	v_mov_b32_e32 v96, v137
	v_mov_b32_e32 v95, v137
	v_mov_b32_e32 v94, v137
	v_mov_b32_e32 v93, v137
	v_mov_b32_e32 v92, v137
	v_mov_b32_e32 v91, v137
	v_mov_b32_e32 v90, v137
	v_mov_b32_e32 v81, v137
	v_mov_b32_e32 v80, v137
	v_mov_b32_e32 v79, v137
	v_mov_b32_e32 v78, v137
	v_mov_b32_e32 v77, v137
	v_mov_b32_e32 v76, v137
	v_mov_b32_e32 v75, v137
	v_mov_b32_e32 v74, v137
	v_mov_b32_e32 v73, v137
	v_mov_b32_e32 v72, v137
	v_mov_b32_e32 v71, v137
	v_mov_b32_e32 v70, v137
	v_mov_b32_e32 v69, v137
	v_mov_b32_e32 v68, v137
	v_mov_b32_e32 v67, v137
	v_mov_b32_e32 v66, v137
	v_mov_b32_e32 v33, v137
	v_mov_b32_e32 v32, v137
	v_mov_b32_e32 v31, v137
	v_mov_b32_e32 v30, v137
	v_mov_b32_e32 v29, v137
	v_mov_b32_e32 v28, v137
	v_mov_b32_e32 v27, v137
	v_mov_b32_e32 v26, v137
	v_mov_b32_e32 v25, v137
	v_mov_b32_e32 v24, v137
	v_mov_b32_e32 v23, v137
	v_mov_b32_e32 v22, v137
	v_mov_b32_e32 v21, v137
	v_mov_b32_e32 v20, v137
	v_mov_b32_e32 v19, v137
	v_mov_b32_e32 v18, v137
	v_mov_b32_e32 v17, v137
	v_mov_b32_e32 v16, v137
	v_mov_b32_e32 v15, v137
	v_mov_b32_e32 v14, v137
	v_mov_b32_e32 v13, v137
	v_mov_b32_e32 v12, v137
	v_mov_b32_e32 v11, v137
	v_mov_b32_e32 v10, v137
	v_mov_b32_e32 v9, v137
	v_mov_b32_e32 v8, v137
	v_mov_b32_e32 v7, v137
	v_mov_b32_e32 v6, v137
	v_mov_b32_e32 v5, v137
	v_mov_b32_e32 v4, v137
	v_mov_b32_e32 v3, v137
	v_mov_b32_e32 v2, v137
	s_branch .LBB0_343
.Lz_enter_339:
	s_add_u32 s16, s16, 0x80
	s_addc_u32 s17, s17, 0
	s_add_u32 s33, s20, 0x100
	v_mov_b32_e32 v2, 0
	s_addc_u32 s39, s21, 0
	s_mov_b32 s20, 0
	v_mov_b32_e32 v3, v2
	v_mov_b32_e32 v4, v2
	v_mov_b32_e32 v5, v2
	v_mov_b32_e32 v6, v2
	v_mov_b32_e32 v7, v2
	v_mov_b32_e32 v8, v2
	v_mov_b32_e32 v9, v2
	v_mov_b32_e32 v10, v2
	v_mov_b32_e32 v11, v2
	v_mov_b32_e32 v12, v2
	v_mov_b32_e32 v13, v2
	v_mov_b32_e32 v14, v2
	v_mov_b32_e32 v15, v2
	v_mov_b32_e32 v16, v2
	v_mov_b32_e32 v17, v2
	v_mov_b32_e32 v18, v2
	v_mov_b32_e32 v19, v2
	v_mov_b32_e32 v20, v2
	v_mov_b32_e32 v21, v2
	v_mov_b32_e32 v22, v2
	v_mov_b32_e32 v23, v2
	v_mov_b32_e32 v24, v2
	v_mov_b32_e32 v25, v2
	v_mov_b32_e32 v26, v2
	v_mov_b32_e32 v27, v2
	v_mov_b32_e32 v28, v2
	v_mov_b32_e32 v29, v2
	v_mov_b32_e32 v30, v2
	v_mov_b32_e32 v31, v2
	v_mov_b32_e32 v32, v2
	v_mov_b32_e32 v33, v2
	v_mov_b32_e32 v66, v2
	v_mov_b32_e32 v67, v2
	v_mov_b32_e32 v68, v2
	v_mov_b32_e32 v69, v2
	v_mov_b32_e32 v70, v2
	v_mov_b32_e32 v71, v2
	v_mov_b32_e32 v72, v2
	v_mov_b32_e32 v73, v2
	v_mov_b32_e32 v74, v2
	v_mov_b32_e32 v75, v2
	v_mov_b32_e32 v76, v2
	v_mov_b32_e32 v77, v2
	v_mov_b32_e32 v78, v2
	v_mov_b32_e32 v79, v2
	v_mov_b32_e32 v80, v2
	v_mov_b32_e32 v81, v2
	v_mov_b32_e32 v90, v2
	v_mov_b32_e32 v91, v2
	v_mov_b32_e32 v92, v2
	v_mov_b32_e32 v93, v2
	v_mov_b32_e32 v94, v2
	v_mov_b32_e32 v95, v2
	v_mov_b32_e32 v96, v2
	v_mov_b32_e32 v97, v2
	v_mov_b32_e32 v98, v2
	v_mov_b32_e32 v99, v2
	v_mov_b32_e32 v100, v2
	v_mov_b32_e32 v101, v2
	v_mov_b32_e32 v102, v2
	v_mov_b32_e32 v103, v2
	v_mov_b32_e32 v104, v2
	v_mov_b32_e32 v105, v2
	v_mov_b32_e32 v34, v2
	v_mov_b32_e32 v35, v2
	v_mov_b32_e32 v36, v2
	v_mov_b32_e32 v37, v2
	v_mov_b32_e32 v38, v2
	v_mov_b32_e32 v39, v2
	v_mov_b32_e32 v40, v2
	v_mov_b32_e32 v41, v2
	v_mov_b32_e32 v42, v2
	v_mov_b32_e32 v43, v2
	v_mov_b32_e32 v44, v2
	v_mov_b32_e32 v45, v2
	v_mov_b32_e32 v46, v2
	v_mov_b32_e32 v47, v2
	v_mov_b32_e32 v48, v2
	v_mov_b32_e32 v49, v2
	v_mov_b32_e32 v50, v2
	v_mov_b32_e32 v51, v2
	v_mov_b32_e32 v52, v2
	v_mov_b32_e32 v53, v2
	v_mov_b32_e32 v54, v2
	v_mov_b32_e32 v55, v2
	v_mov_b32_e32 v56, v2
	v_mov_b32_e32 v57, v2
	v_mov_b32_e32 v58, v2
	v_mov_b32_e32 v59, v2
	v_mov_b32_e32 v60, v2
	v_mov_b32_e32 v61, v2
	v_mov_b32_e32 v62, v2
	v_mov_b32_e32 v63, v2
	v_mov_b32_e32 v64, v2
	v_mov_b32_e32 v65, v2
	v_mov_b32_e32 v106, v2
	v_mov_b32_e32 v107, v2
	v_mov_b32_e32 v108, v2
	v_mov_b32_e32 v109, v2
	v_mov_b32_e32 v110, v2
	v_mov_b32_e32 v111, v2
	v_mov_b32_e32 v112, v2
	v_mov_b32_e32 v113, v2
	v_mov_b32_e32 v114, v2
	v_mov_b32_e32 v115, v2
	v_mov_b32_e32 v116, v2
	v_mov_b32_e32 v117, v2
	v_mov_b32_e32 v118, v2
	v_mov_b32_e32 v119, v2
	v_mov_b32_e32 v120, v2
	v_mov_b32_e32 v121, v2
	v_mov_b32_e32 v122, v2
	v_mov_b32_e32 v123, v2
	v_mov_b32_e32 v124, v2
	v_mov_b32_e32 v125, v2
	v_mov_b32_e32 v126, v2
	v_mov_b32_e32 v127, v2
	v_mov_b32_e32 v128, v2
	v_mov_b32_e32 v129, v2
	v_mov_b32_e32 v130, v2
	v_mov_b32_e32 v131, v2
	v_mov_b32_e32 v132, v2
	v_mov_b32_e32 v133, v2
	v_mov_b32_e32 v134, v2
	v_mov_b32_e32 v135, v2
	v_mov_b32_e32 v136, v2
	v_mov_b32_e32 v137, v2

; template <class Epi, class Sched, bool ALIGN_EPI = false, bool SP2 = false>
; __device__ __forceinline__ void gemm_phase(PG8_LAS unsigned char* lds, const Gemm g, const Sched& S, const Epi& E) {
;     ...
;         for (int t = 0; t < nt; t += 2) {
;             const bool last = (t == nt - 2);
;             const char* a1 = cA + (size_t)(t + 1) * kstep;
;             const char* a2 = last ? nA : cA + (size_t)(t + 2) * kstep; const char* b2 = last ? nB : cB + (size_t)(t + 2) * kstep;
;             const char* a3 = a2 + kstep; const char* b3 = b2 + kstep;
;     ...
; #pragma unroll
;         for (int a = 0; a < 2; ++a)
; #pragma unroll
;             for (int b = 0; b < 2; ++b)
; #pragma unroll
;                 for (int m = 0; m < 4; ++m)
; #pragma unroll
;                     for (int n = 0; n < 2; ++n) acc[a][b][m][n] = (f32x4){0.f, 0.f, 0.f, 0.f};
;         cur = nxt; cA = nA; cB = nB; ++ui;
.LBB0_518:
	s_andn2_b64 vcc, exec, s[44:45]
	s_cbranch_vccz .Lz_enter_518
	v_mov_b32_e32 v129, 0
	v_mov_b32_e32 v128, v129
	v_mov_b32_e32 v127, v129
	v_mov_b32_e32 v126, v129
	v_mov_b32_e32 v125, v129
	v_mov_b32_e32 v124, v129
	v_mov_b32_e32 v123, v129
	v_mov_b32_e32 v122, v129
	v_mov_b32_e32 v113, v129
	v_mov_b32_e32 v112, v129
	v_mov_b32_e32 v111, v129
	v_mov_b32_e32 v110, v129
	v_mov_b32_e32 v109, v129
	v_mov_b32_e32 v108, v129
	v_mov_b32_e32 v107, v129
	v_mov_b32_e32 v106, v129
	v_mov_b32_e32 v97, v129
	v_mov_b32_e32 v96, v129
	v_mov_b32_e32 v95, v129
	v_mov_b32_e32 v94, v129
	v_mov_b32_e32 v93, v129
	v_mov_b32_e32 v92, v129
	v_mov_b32_e32 v91, v129
	v_mov_b32_e32 v90, v129
	v_mov_b32_e32 v81, v129
	v_mov_b32_e32 v80, v129
	v_mov_b32_e32 v79, v129
	v_mov_b32_e32 v78, v129
	v_mov_b32_e32 v77, v129
	v_mov_b32_e32 v76, v129
	v_mov_b32_e32 v75, v129
	v_mov_b32_e32 v74, v129
	v_mov_b32_e32 v121, v129
	v_mov_b32_e32 v120, v129
	v_mov_b32_e32 v119, v129
	v_mov_b32_e32 v118, v129
	v_mov_b32_e32 v117, v129
	v_mov_b32_e32 v116, v129
	v_mov_b32_e32 v115, v129
	v_mov_b32_e32 v114, v129
	v_mov_b32_e32 v105, v129
	v_mov_b32_e32 v104, v129
	v_mov_b32_e32 v103, v129
	v_mov_b32_e32 v102, v129
	v_mov_b32_e32 v101, v129
	v_mov_b32_e32 v100, v129
	v_mov_b32_e32 v99, v129
	v_mov_b32_e32 v98, v129
	v_mov_b32_e32 v89, v129
	v_mov_b32_e32 v88, v129
	v_mov_b32_e32 v87, v129
	v_mov_b32_e32 v86, v129
	v_mov_b32_e32 v85, v129
	v_mov_b32_e32 v84, v129
	v_mov_b32_e32 v83, v129
	v_mov_b32_e32 v82, v129
	v_mov_b32_e32 v73, v129
	v_mov_b32_e32 v72, v129
	v_mov_b32_e32 v71, v129
	v_mov_b32_e32 v70, v129
	v_mov_b32_e32 v69, v129
	v_mov_b32_e32 v68, v129
	v_mov_b32_e32 v67, v129
	v_mov_b32_e32 v66, v129
	v_mov_b32_e32 v65, v129
	v_mov_b32_e32 v64, v129
	v_mov_b32_e32 v63, v129
	v_mov_b32_e32 v62, v129
	v_mov_b32_e32 v61, v129
	v_mov_b32_e32 v60, v129
	v_mov_b32_e32 v59, v129
	v_mov_b32_e32 v58, v129
	v_mov_b32_e32 v49, v129
	v_mov_b32_e32 v48, v129
	v_mov_b32_e32 v47, v129
	v_mov_b32_e32 v46, v129
	v_mov_b32_e32 v45, v129
	v_mov_b32_e32 v44, v129
	v_mov_b32_e32 v43, v129
	v_mov_b32_e32 v42, v129
	v_mov_b32_e32 v33, v129
	v_mov_b32_e32 v32, v129
	v_mov_b32_e32 v31, v129
	v_mov_b32_e32 v30, v129
	v_mov_b32_e32 v29, v129
	v_mov_b32_e32 v28, v129
	v_mov_b32_e32 v27, v129
	v_mov_b32_e32 v26, v129
	v_mov_b32_e32 v17, v129
	v_mov_b32_e32 v16, v129
	v_mov_b32_e32 v15, v129
	v_mov_b32_e32 v14, v129
	v_mov_b32_e32 v13, v129
	v_mov_b32_e32 v12, v129
	v_mov_b32_e32 v11, v129
	v_mov_b32_e32 v10, v129
	v_mov_b32_e32 v57, v129
	v_mov_b32_e32 v56, v129
	v_mov_b32_e32 v55, v129
	v_mov_b32_e32 v54, v129
	v_mov_b32_e32 v53, v129
	v_mov_b32_e32 v52, v129
	v_mov_b32_e32 v51, v129
	v_mov_b32_e32 v50, v129
	v_mov_b32_e32 v41, v129
	v_mov_b32_e32 v40, v129
	v_mov_b32_e32 v39, v129
	v_mov_b32_e32 v38, v129
	v_mov_b32_e32 v37, v129
	v_mov_b32_e32 v36, v129
	v_mov_b32_e32 v35, v129
	v_mov_b32_e32 v34, v129
	v_mov_b32_e32 v25, v129
	v_mov_b32_e32 v24, v129
	v_mov_b32_e32 v23, v129
	v_mov_b32_e32 v22, v129
	v_mov_b32_e32 v21, v129
	v_mov_b32_e32 v20, v129
	v_mov_b32_e32 v19, v129
	v_mov_b32_e32 v18, v129
	v_mov_b32_e32 v9, v129
	v_mov_b32_e32 v8, v129
	v_mov_b32_e32 v7, v129
	v_mov_b32_e32 v6, v129
	v_mov_b32_e32 v5, v129
	v_mov_b32_e32 v4, v129
	v_mov_b32_e32 v3, v129
	v_mov_b32_e32 v2, v129
	s_branch .LBB0_521
.Lz_enter_518:
	s_add_u32 s8, s52, 0x80
	s_addc_u32 s9, s53, 0
	s_add_u32 s52, s20, 0x100
	v_mov_b32_e32 v2, 0
	s_addc_u32 s53, s21, 0
	s_mov_b32 s20, 0
	v_mov_b32_e32 v3, v2
	v_mov_b32_e32 v4, v2
	v_mov_b32_e32 v5, v2
	v_mov_b32_e32 v6, v2
	v_mov_b32_e32 v7, v2
	v_mov_b32_e32 v8, v2
	v_mov_b32_e32 v9, v2
	v_mov_b32_e32 v18, v2
	v_mov_b32_e32 v19, v2
	v_mov_b32_e32 v20, v2
	v_mov_b32_e32 v21, v2
	v_mov_b32_e32 v22, v2
	v_mov_b32_e32 v23, v2
	v_mov_b32_e32 v24, v2
	v_mov_b32_e32 v25, v2
	v_mov_b32_e32 v34, v2
	v_mov_b32_e32 v35, v2
	v_mov_b32_e32 v36, v2
	v_mov_b32_e32 v37, v2
	v_mov_b32_e32 v38, v2
	v_mov_b32_e32 v39, v2
	v_mov_b32_e32 v40, v2
	v_mov_b32_e32 v41, v2
	v_mov_b32_e32 v50, v2
	v_mov_b32_e32 v51, v2
	v_mov_b32_e32 v52, v2
	v_mov_b32_e32 v53, v2
	v_mov_b32_e32 v54, v2
	v_mov_b32_e32 v55, v2
	v_mov_b32_e32 v56, v2
	v_mov_b32_e32 v57, v2
	v_mov_b32_e32 v10, v2
	v_mov_b32_e32 v11, v2
	v_mov_b32_e32 v12, v2
	v_mov_b32_e32 v13, v2
	v_mov_b32_e32 v14, v2
	v_mov_b32_e32 v15, v2
	v_mov_b32_e32 v16, v2
	v_mov_b32_e32 v17, v2
	v_mov_b32_e32 v26, v2
	v_mov_b32_e32 v27, v2
	v_mov_b32_e32 v28, v2
	v_mov_b32_e32 v29, v2
	v_mov_b32_e32 v30, v2
	v_mov_b32_e32 v31, v2
	v_mov_b32_e32 v32, v2
	v_mov_b32_e32 v33, v2
	v_mov_b32_e32 v42, v2
	v_mov_b32_e32 v43, v2
	v_mov_b32_e32 v44, v2
	v_mov_b32_e32 v45, v2
	v_mov_b32_e32 v46, v2
	v_mov_b32_e32 v47, v2
	v_mov_b32_e32 v48, v2
	v_mov_b32_e32 v49, v2
	v_mov_b32_e32 v58, v2
	v_mov_b32_e32 v59, v2
	v_mov_b32_e32 v60, v2
	v_mov_b32_e32 v61, v2
	v_mov_b32_e32 v62, v2
	v_mov_b32_e32 v63, v2
	v_mov_b32_e32 v64, v2
	v_mov_b32_e32 v65, v2
	v_mov_b32_e32 v66, v2
	v_mov_b32_e32 v67, v2
	v_mov_b32_e32 v68, v2
	v_mov_b32_e32 v69, v2
	v_mov_b32_e32 v70, v2
	v_mov_b32_e32 v71, v2
	v_mov_b32_e32 v72, v2
	v_mov_b32_e32 v73, v2
	v_mov_b32_e32 v82, v2
	v_mov_b32_e32 v83, v2
	v_mov_b32_e32 v84, v2
	v_mov_b32_e32 v85, v2
	v_mov_b32_e32 v86, v2
	v_mov_b32_e32 v87, v2
	v_mov_b32_e32 v88, v2
	v_mov_b32_e32 v89, v2
	v_mov_b32_e32 v98, v2
	v_mov_b32_e32 v99, v2
	v_mov_b32_e32 v100, v2
	v_mov_b32_e32 v101, v2
	v_mov_b32_e32 v102, v2
	v_mov_b32_e32 v103, v2
	v_mov_b32_e32 v104, v2
	v_mov_b32_e32 v105, v2
	v_mov_b32_e32 v114, v2
	v_mov_b32_e32 v115, v2
	v_mov_b32_e32 v116, v2
	v_mov_b32_e32 v117, v2
	v_mov_b32_e32 v118, v2
	v_mov_b32_e32 v119, v2
	v_mov_b32_e32 v120, v2
	v_mov_b32_e32 v121, v2
	v_mov_b32_e32 v74, v2
	v_mov_b32_e32 v75, v2
	v_mov_b32_e32 v76, v2
	v_mov_b32_e32 v77, v2
	v_mov_b32_e32 v78, v2
	v_mov_b32_e32 v79, v2
	v_mov_b32_e32 v80, v2
	v_mov_b32_e32 v81, v2
	v_mov_b32_e32 v90, v2
	v_mov_b32_e32 v91, v2
	v_mov_b32_e32 v92, v2
	v_mov_b32_e32 v93, v2
	v_mov_b32_e32 v94, v2
	v_mov_b32_e32 v95, v2
	v_mov_b32_e32 v96, v2
	v_mov_b32_e32 v97, v2
	v_mov_b32_e32 v106, v2
	v_mov_b32_e32 v107, v2
	v_mov_b32_e32 v108, v2
	v_mov_b32_e32 v109, v2
	v_mov_b32_e32 v110, v2
	v_mov_b32_e32 v111, v2
	v_mov_b32_e32 v112, v2
	v_mov_b32_e32 v113, v2
	v_mov_b32_e32 v122, v2
	v_mov_b32_e32 v123, v2
	v_mov_b32_e32 v124, v2
	v_mov_b32_e32 v125, v2
	v_mov_b32_e32 v126, v2
	v_mov_b32_e32 v127, v2
	v_mov_b32_e32 v128, v2
	v_mov_b32_e32 v129, v2

; template <class Epi, class Sched, bool ALIGN_EPI = false, bool SP2 = false>
; __device__ __forceinline__ void gemm_phase(PG8_LAS unsigned char* lds, const Gemm g, const Sched& S, const Epi& E) {
;     ...
;         for (int t = 0; t < nt; t += 2) {
;             const bool last = (t == nt - 2);
;             const char* a1 = cA + (size_t)(t + 1) * kstep;
;             const char* a2 = last ? nA : cA + (size_t)(t + 2) * kstep; const char* b2 = last ? nB : cB + (size_t)(t + 2) * kstep;
;             const char* a3 = a2 + kstep; const char* b3 = b2 + kstep;
;     ...
; #pragma unroll
;         for (int a = 0; a < 2; ++a)
; #pragma unroll
;             for (int b = 0; b < 2; ++b)
; #pragma unroll
;                 for (int m = 0; m < 4; ++m)
; #pragma unroll
;                     for (int n = 0; n < 2; ++n) acc[a][b][m][n] = (f32x4){0.f, 0.f, 0.f, 0.f};
;         cur = nxt; cA = nA; cB = nB; ++ui;
.LBB0_568:
	s_andn2_b64 vcc, exec, s[50:51]
	s_waitcnt vmcnt(0)
	s_cbranch_vccz .Lz_enter_568
	v_mov_b32_e32 v145, 0
	v_mov_b32_e32 v144, v145
	v_mov_b32_e32 v143, v145
	v_mov_b32_e32 v142, v145
	v_mov_b32_e32 v141, v145
	v_mov_b32_e32 v140, v145
	v_mov_b32_e32 v139, v145
	v_mov_b32_e32 v138, v145
	v_mov_b32_e32 v129, v145
	v_mov_b32_e32 v128, v145
	v_mov_b32_e32 v127, v145
	v_mov_b32_e32 v126, v145
	v_mov_b32_e32 v125, v145
	v_mov_b32_e32 v124, v145
	v_mov_b32_e32 v123, v145
	v_mov_b32_e32 v122, v145
	v_mov_b32_e32 v113, v145
	v_mov_b32_e32 v112, v145
	v_mov_b32_e32 v111, v145
	v_mov_b32_e32 v110, v145
	v_mov_b32_e32 v97, v145
	v_mov_b32_e32 v96, v145
	v_mov_b32_e32 v95, v145
	v_mov_b32_e32 v94, v145
	v_mov_b32_e32 v81, v145
	v_mov_b32_e32 v80, v145
	v_mov_b32_e32 v79, v145
	v_mov_b32_e32 v78, v145
	v_mov_b32_e32 v77, v145
	v_mov_b32_e32 v76, v145
	v_mov_b32_e32 v75, v145
	v_mov_b32_e32 v74, v145
	v_mov_b32_e32 v137, v145
	v_mov_b32_e32 v136, v145
	v_mov_b32_e32 v135, v145
	v_mov_b32_e32 v134, v145
	v_mov_b32_e32 v133, v145
	v_mov_b32_e32 v132, v145
	v_mov_b32_e32 v131, v145
	v_mov_b32_e32 v130, v145
	v_mov_b32_e32 v121, v145
	v_mov_b32_e32 v120, v145
	v_mov_b32_e32 v119, v145
	v_mov_b32_e32 v118, v145
	v_mov_b32_e32 v117, v145
	v_mov_b32_e32 v116, v145
	v_mov_b32_e32 v115, v145
	v_mov_b32_e32 v114, v145
	v_mov_b32_e32 v93, v145
	v_mov_b32_e32 v92, v145
	v_mov_b32_e32 v91, v145
	v_mov_b32_e32 v90, v145
	v_mov_b32_e32 v89, v145
	v_mov_b32_e32 v88, v145
	v_mov_b32_e32 v87, v145
	v_mov_b32_e32 v86, v145
	v_mov_b32_e32 v73, v145
	v_mov_b32_e32 v72, v145
	v_mov_b32_e32 v71, v145
	v_mov_b32_e32 v70, v145
	v_mov_b32_e32 v69, v145
	v_mov_b32_e32 v68, v145
	v_mov_b32_e32 v67, v145
	v_mov_b32_e32 v66, v145
	v_mov_b32_e32 v65, v145
	v_mov_b32_e32 v64, v145
	v_mov_b32_e32 v63, v145
	v_mov_b32_e32 v62, v145
	v_mov_b32_e32 v61, v145
	v_mov_b32_e32 v60, v145
	v_mov_b32_e32 v59, v145
	v_mov_b32_e32 v58, v145
	v_mov_b32_e32 v49, v145
	v_mov_b32_e32 v48, v145
	v_mov_b32_e32 v47, v145
	v_mov_b32_e32 v46, v145
	v_mov_b32_e32 v45, v145
	v_mov_b32_e32 v44, v145
	v_mov_b32_e32 v43, v145
	v_mov_b32_e32 v42, v145
	v_mov_b32_e32 v33, v145
	v_mov_b32_e32 v32, v145
	v_mov_b32_e32 v31, v145
	v_mov_b32_e32 v30, v145
	v_mov_b32_e32 v29, v145
	v_mov_b32_e32 v28, v145
	v_mov_b32_e32 v27, v145
	v_mov_b32_e32 v26, v145
	v_mov_b32_e32 v17, v145
	v_mov_b32_e32 v16, v145
	v_mov_b32_e32 v15, v145
	v_mov_b32_e32 v14, v145
	v_mov_b32_e32 v13, v145
	v_mov_b32_e32 v12, v145
	v_mov_b32_e32 v11, v145
	v_mov_b32_e32 v10, v145
	v_mov_b32_e32 v57, v145
	v_mov_b32_e32 v56, v145
	v_mov_b32_e32 v55, v145
	v_mov_b32_e32 v54, v145
	v_mov_b32_e32 v53, v145
	v_mov_b32_e32 v52, v145
	v_mov_b32_e32 v51, v145
	v_mov_b32_e32 v50, v145
	v_mov_b32_e32 v41, v145
	v_mov_b32_e32 v40, v145
	v_mov_b32_e32 v39, v145
	v_mov_b32_e32 v38, v145
	v_mov_b32_e32 v37, v145
	v_mov_b32_e32 v36, v145
	v_mov_b32_e32 v35, v145
	v_mov_b32_e32 v34, v145
	v_mov_b32_e32 v25, v145
	v_mov_b32_e32 v24, v145
	v_mov_b32_e32 v23, v145
	v_mov_b32_e32 v22, v145
	v_mov_b32_e32 v21, v145
	v_mov_b32_e32 v20, v145
	v_mov_b32_e32 v19, v145
	v_mov_b32_e32 v18, v145
	v_mov_b32_e32 v9, v145
	v_mov_b32_e32 v8, v145
	v_mov_b32_e32 v7, v145
	v_mov_b32_e32 v6, v145
	v_mov_b32_e32 v5, v145
	v_mov_b32_e32 v4, v145
	v_mov_b32_e32 v3, v145
	v_mov_b32_e32 v2, v145
	s_branch .LBB0_571
.Lz_enter_568:
	s_add_u32 s10, s62, 0x80
	s_addc_u32 s11, s63, 0
	s_add_u32 s62, s20, 0x100
	v_mov_b32_e32 v2, 0
	s_addc_u32 s63, s21, 0
	s_mov_b32 s20, 0
	v_mov_b32_e32 v3, v2
	v_mov_b32_e32 v4, v2
	v_mov_b32_e32 v5, v2
	v_mov_b32_e32 v6, v2
	v_mov_b32_e32 v7, v2
	v_mov_b32_e32 v8, v2
	v_mov_b32_e32 v9, v2
	v_mov_b32_e32 v18, v2
	v_mov_b32_e32 v19, v2
	v_mov_b32_e32 v20, v2
	v_mov_b32_e32 v21, v2
	v_mov_b32_e32 v22, v2
	v_mov_b32_e32 v23, v2
	v_mov_b32_e32 v24, v2
	v_mov_b32_e32 v25, v2
	v_mov_b32_e32 v34, v2
	v_mov_b32_e32 v35, v2
	v_mov_b32_e32 v36, v2
	v_mov_b32_e32 v37, v2
	v_mov_b32_e32 v38, v2
	v_mov_b32_e32 v39, v2
	v_mov_b32_e32 v40, v2
	v_mov_b32_e32 v41, v2
	v_mov_b32_e32 v50, v2
	v_mov_b32_e32 v51, v2
	v_mov_b32_e32 v52, v2
	v_mov_b32_e32 v53, v2
	v_mov_b32_e32 v54, v2
	v_mov_b32_e32 v55, v2
	v_mov_b32_e32 v56, v2
	v_mov_b32_e32 v57, v2
	v_mov_b32_e32 v10, v2
	v_mov_b32_e32 v11, v2
	v_mov_b32_e32 v12, v2
	v_mov_b32_e32 v13, v2
	v_mov_b32_e32 v14, v2
	v_mov_b32_e32 v15, v2
	v_mov_b32_e32 v16, v2
	v_mov_b32_e32 v17, v2
	v_mov_b32_e32 v26, v2
	v_mov_b32_e32 v27, v2
	v_mov_b32_e32 v28, v2
	v_mov_b32_e32 v29, v2
	v_mov_b32_e32 v30, v2
	v_mov_b32_e32 v31, v2
	v_mov_b32_e32 v32, v2
	v_mov_b32_e32 v33, v2
	v_mov_b32_e32 v42, v2
	v_mov_b32_e32 v43, v2
	v_mov_b32_e32 v44, v2
	v_mov_b32_e32 v45, v2
	v_mov_b32_e32 v46, v2
	v_mov_b32_e32 v47, v2
	v_mov_b32_e32 v48, v2
	v_mov_b32_e32 v49, v2
	v_mov_b32_e32 v58, v2
	v_mov_b32_e32 v59, v2
	v_mov_b32_e32 v60, v2
	v_mov_b32_e32 v61, v2
	v_mov_b32_e32 v62, v2
	v_mov_b32_e32 v63, v2
	v_mov_b32_e32 v64, v2
	v_mov_b32_e32 v65, v2
	v_mov_b32_e32 v66, v2
	v_mov_b32_e32 v67, v2
	v_mov_b32_e32 v68, v2
	v_mov_b32_e32 v69, v2
	v_mov_b32_e32 v70, v2
	v_mov_b32_e32 v71, v2
	v_mov_b32_e32 v72, v2
	v_mov_b32_e32 v73, v2
	v_mov_b32_e32 v86, v2
	v_mov_b32_e32 v87, v2
	v_mov_b32_e32 v88, v2
	v_mov_b32_e32 v89, v2
	v_mov_b32_e32 v90, v2
	v_mov_b32_e32 v91, v2
	v_mov_b32_e32 v92, v2
	v_mov_b32_e32 v93, v2
	v_mov_b32_e32 v114, v2
	v_mov_b32_e32 v115, v2
	v_mov_b32_e32 v116, v2
	v_mov_b32_e32 v117, v2
	v_mov_b32_e32 v118, v2
	v_mov_b32_e32 v119, v2
	v_mov_b32_e32 v120, v2
	v_mov_b32_e32 v121, v2
	v_mov_b32_e32 v130, v2
	v_mov_b32_e32 v131, v2
	v_mov_b32_e32 v132, v2
	v_mov_b32_e32 v133, v2
	v_mov_b32_e32 v134, v2
	v_mov_b32_e32 v135, v2
	v_mov_b32_e32 v136, v2
	v_mov_b32_e32 v137, v2
	v_mov_b32_e32 v74, v2
	v_mov_b32_e32 v75, v2
	v_mov_b32_e32 v76, v2
	v_mov_b32_e32 v77, v2
	v_mov_b32_e32 v78, v2
	v_mov_b32_e32 v79, v2
	v_mov_b32_e32 v80, v2
	v_mov_b32_e32 v81, v2
	v_mov_b32_e32 v94, v2
	v_mov_b32_e32 v95, v2
	v_mov_b32_e32 v96, v2
	v_mov_b32_e32 v97, v2
	v_mov_b32_e32 v110, v2
	v_mov_b32_e32 v111, v2
	v_mov_b32_e32 v112, v2
	v_mov_b32_e32 v113, v2
	v_mov_b32_e32 v122, v2
	v_mov_b32_e32 v123, v2
	v_mov_b32_e32 v124, v2
	v_mov_b32_e32 v125, v2
	v_mov_b32_e32 v126, v2
	v_mov_b32_e32 v127, v2
	v_mov_b32_e32 v128, v2
	v_mov_b32_e32 v129, v2
	v_mov_b32_e32 v138, v2
	v_mov_b32_e32 v139, v2
	v_mov_b32_e32 v140, v2
	v_mov_b32_e32 v141, v2
	v_mov_b32_e32 v142, v2
	v_mov_b32_e32 v143, v2
	v_mov_b32_e32 v144, v2
	v_mov_b32_e32 v145, v2

; template <class Epi, class Sched, bool ALIGN_EPI = false, bool SP2 = false>
; __device__ __forceinline__ void gemm_phase(PG8_LAS unsigned char* lds, const Gemm g, const Sched& S, const Epi& E) {
;     ...
;         for (int t = 0; t < nt; t += 2) {
;             const bool last = (t == nt - 2);
;             const char* a1 = cA + (size_t)(t + 1) * kstep;
;             const char* a2 = last ? nA : cA + (size_t)(t + 2) * kstep; const char* b2 = last ? nB : cB + (size_t)(t + 2) * kstep;
;             const char* a3 = a2 + kstep; const char* b3 = b2 + kstep;
;     ...
; #pragma unroll
;         for (int a = 0; a < 2; ++a)
; #pragma unroll
;             for (int b = 0; b < 2; ++b)
; #pragma unroll
;                 for (int m = 0; m < 4; ++m)
; #pragma unroll
;                     for (int n = 0; n < 2; ++n) acc[a][b][m][n] = (f32x4){0.f, 0.f, 0.f, 0.f};
;         cur = nxt; cA = nA; cB = nB; ++ui;
.LBB0_639:
	s_andn2_b64 vcc, exec, s[44:45]
	s_cbranch_vccz .Lz_enter_639
	v_mov_b32_e32 v125, 0
	v_mov_b32_e32 v124, v125
	v_mov_b32_e32 v123, v125
	v_mov_b32_e32 v122, v125
	v_mov_b32_e32 v121, v125
	v_mov_b32_e32 v120, v125
	v_mov_b32_e32 v119, v125
	v_mov_b32_e32 v118, v125
	v_mov_b32_e32 v109, v125
	v_mov_b32_e32 v108, v125
	v_mov_b32_e32 v107, v125
	v_mov_b32_e32 v106, v125
	v_mov_b32_e32 v105, v125
	v_mov_b32_e32 v104, v125
	v_mov_b32_e32 v103, v125
	v_mov_b32_e32 v102, v125
	v_mov_b32_e32 v93, v125
	v_mov_b32_e32 v92, v125
	v_mov_b32_e32 v91, v125
	v_mov_b32_e32 v90, v125
	v_mov_b32_e32 v89, v125
	v_mov_b32_e32 v88, v125
	v_mov_b32_e32 v87, v125
	v_mov_b32_e32 v86, v125
	v_mov_b32_e32 v77, v125
	v_mov_b32_e32 v76, v125
	v_mov_b32_e32 v75, v125
	v_mov_b32_e32 v74, v125
	v_mov_b32_e32 v73, v125
	v_mov_b32_e32 v72, v125
	v_mov_b32_e32 v71, v125
	v_mov_b32_e32 v70, v125
	v_mov_b32_e32 v129, v125
	v_mov_b32_e32 v128, v125
	v_mov_b32_e32 v127, v125
	v_mov_b32_e32 v126, v125
	v_mov_b32_e32 v117, v125
	v_mov_b32_e32 v116, v125
	v_mov_b32_e32 v115, v125
	v_mov_b32_e32 v114, v125
	v_mov_b32_e32 v113, v125
	v_mov_b32_e32 v112, v125
	v_mov_b32_e32 v111, v125
	v_mov_b32_e32 v110, v125
	v_mov_b32_e32 v101, v125
	v_mov_b32_e32 v100, v125
	v_mov_b32_e32 v99, v125
	v_mov_b32_e32 v98, v125
	v_mov_b32_e32 v97, v125
	v_mov_b32_e32 v96, v125
	v_mov_b32_e32 v95, v125
	v_mov_b32_e32 v94, v125
	v_mov_b32_e32 v85, v125
	v_mov_b32_e32 v84, v125
	v_mov_b32_e32 v83, v125
	v_mov_b32_e32 v82, v125
	v_mov_b32_e32 v81, v125
	v_mov_b32_e32 v80, v125
	v_mov_b32_e32 v79, v125
	v_mov_b32_e32 v78, v125
	v_mov_b32_e32 v69, v125
	v_mov_b32_e32 v68, v125
	v_mov_b32_e32 v67, v125
	v_mov_b32_e32 v66, v125
	v_mov_b32_e32 v61, v125
	v_mov_b32_e32 v60, v125
	v_mov_b32_e32 v59, v125
	v_mov_b32_e32 v58, v125
	v_mov_b32_e32 v57, v125
	v_mov_b32_e32 v56, v125
	v_mov_b32_e32 v55, v125
	v_mov_b32_e32 v54, v125
	v_mov_b32_e32 v45, v125
	v_mov_b32_e32 v44, v125
	v_mov_b32_e32 v43, v125
	v_mov_b32_e32 v42, v125
	v_mov_b32_e32 v41, v125
	v_mov_b32_e32 v40, v125
	v_mov_b32_e32 v39, v125
	v_mov_b32_e32 v38, v125
	v_mov_b32_e32 v29, v125
	v_mov_b32_e32 v28, v125
	v_mov_b32_e32 v27, v125
	v_mov_b32_e32 v26, v125
	v_mov_b32_e32 v25, v125
	v_mov_b32_e32 v24, v125
	v_mov_b32_e32 v23, v125
	v_mov_b32_e32 v22, v125
	v_mov_b32_e32 v13, v125
	v_mov_b32_e32 v12, v125
	v_mov_b32_e32 v11, v125
	v_mov_b32_e32 v10, v125
	v_mov_b32_e32 v9, v125
	v_mov_b32_e32 v8, v125
	v_mov_b32_e32 v7, v125
	v_mov_b32_e32 v6, v125
	v_mov_b32_e32 v65, v125
	v_mov_b32_e32 v64, v125
	v_mov_b32_e32 v63, v125
	v_mov_b32_e32 v62, v125
	v_mov_b32_e32 v53, v125
	v_mov_b32_e32 v52, v125
	v_mov_b32_e32 v51, v125
	v_mov_b32_e32 v50, v125
	v_mov_b32_e32 v49, v125
	v_mov_b32_e32 v48, v125
	v_mov_b32_e32 v47, v125
	v_mov_b32_e32 v46, v125
	v_mov_b32_e32 v37, v125
	v_mov_b32_e32 v36, v125
	v_mov_b32_e32 v35, v125
	v_mov_b32_e32 v34, v125
	v_mov_b32_e32 v33, v125
	v_mov_b32_e32 v32, v125
	v_mov_b32_e32 v31, v125
	v_mov_b32_e32 v30, v125
	v_mov_b32_e32 v21, v125
	v_mov_b32_e32 v20, v125
	v_mov_b32_e32 v19, v125
	v_mov_b32_e32 v18, v125
	v_mov_b32_e32 v17, v125
	v_mov_b32_e32 v16, v125
	v_mov_b32_e32 v15, v125
	v_mov_b32_e32 v14, v125
	v_mov_b32_e32 v5, v125
	v_mov_b32_e32 v4, v125
	v_mov_b32_e32 v3, v125
	v_mov_b32_e32 v2, v125
	s_branch .LBB0_642
.Lz_enter_639:
	s_add_u32 s8, s52, 0x80
	s_addc_u32 s9, s53, 0
	s_add_u32 s52, s20, 0x100
	v_mov_b32_e32 v2, 0
	s_addc_u32 s53, s21, 0
	s_mov_b32 s20, 0
	v_mov_b32_e32 v3, v2
	v_mov_b32_e32 v4, v2
	v_mov_b32_e32 v5, v2
	v_mov_b32_e32 v14, v2
	v_mov_b32_e32 v15, v2
	v_mov_b32_e32 v16, v2
	v_mov_b32_e32 v17, v2
	v_mov_b32_e32 v18, v2
	v_mov_b32_e32 v19, v2
	v_mov_b32_e32 v20, v2
	v_mov_b32_e32 v21, v2
	v_mov_b32_e32 v30, v2
	v_mov_b32_e32 v31, v2
	v_mov_b32_e32 v32, v2
	v_mov_b32_e32 v33, v2
	v_mov_b32_e32 v34, v2
	v_mov_b32_e32 v35, v2
	v_mov_b32_e32 v36, v2
	v_mov_b32_e32 v37, v2
	v_mov_b32_e32 v46, v2
	v_mov_b32_e32 v47, v2
	v_mov_b32_e32 v48, v2
	v_mov_b32_e32 v49, v2
	v_mov_b32_e32 v50, v2
	v_mov_b32_e32 v51, v2
	v_mov_b32_e32 v52, v2
	v_mov_b32_e32 v53, v2
	v_mov_b32_e32 v62, v2
	v_mov_b32_e32 v63, v2
	v_mov_b32_e32 v64, v2
	v_mov_b32_e32 v65, v2
	v_mov_b32_e32 v6, v2
	v_mov_b32_e32 v7, v2
	v_mov_b32_e32 v8, v2
	v_mov_b32_e32 v9, v2
	v_mov_b32_e32 v10, v2
	v_mov_b32_e32 v11, v2
	v_mov_b32_e32 v12, v2
	v_mov_b32_e32 v13, v2
	v_mov_b32_e32 v22, v2
	v_mov_b32_e32 v23, v2
	v_mov_b32_e32 v24, v2
	v_mov_b32_e32 v25, v2
	v_mov_b32_e32 v26, v2
	v_mov_b32_e32 v27, v2
	v_mov_b32_e32 v28, v2
	v_mov_b32_e32 v29, v2
	v_mov_b32_e32 v38, v2
	v_mov_b32_e32 v39, v2
	v_mov_b32_e32 v40, v2
	v_mov_b32_e32 v41, v2
	v_mov_b32_e32 v42, v2
	v_mov_b32_e32 v43, v2
	v_mov_b32_e32 v44, v2
	v_mov_b32_e32 v45, v2
	v_mov_b32_e32 v54, v2
	v_mov_b32_e32 v55, v2
	v_mov_b32_e32 v56, v2
	v_mov_b32_e32 v57, v2
	v_mov_b32_e32 v58, v2
	v_mov_b32_e32 v59, v2
	v_mov_b32_e32 v60, v2
	v_mov_b32_e32 v61, v2
	v_mov_b32_e32 v66, v2
	v_mov_b32_e32 v67, v2
	v_mov_b32_e32 v68, v2
	v_mov_b32_e32 v69, v2
	v_mov_b32_e32 v78, v2
	v_mov_b32_e32 v79, v2
	v_mov_b32_e32 v80, v2
	v_mov_b32_e32 v81, v2
	v_mov_b32_e32 v82, v2
	v_mov_b32_e32 v83, v2
	v_mov_b32_e32 v84, v2
	v_mov_b32_e32 v85, v2
	v_mov_b32_e32 v94, v2
	v_mov_b32_e32 v95, v2
	v_mov_b32_e32 v96, v2
	v_mov_b32_e32 v97, v2
	v_mov_b32_e32 v98, v2
	v_mov_b32_e32 v99, v2
	v_mov_b32_e32 v100, v2
	v_mov_b32_e32 v101, v2
	v_mov_b32_e32 v110, v2
	v_mov_b32_e32 v111, v2
	v_mov_b32_e32 v112, v2
	v_mov_b32_e32 v113, v2
	v_mov_b32_e32 v114, v2
	v_mov_b32_e32 v115, v2
	v_mov_b32_e32 v116, v2
	v_mov_b32_e32 v117, v2
	v_mov_b32_e32 v126, v2
	v_mov_b32_e32 v127, v2
	v_mov_b32_e32 v128, v2
	v_mov_b32_e32 v129, v2
	v_mov_b32_e32 v70, v2
	v_mov_b32_e32 v71, v2
	v_mov_b32_e32 v72, v2
	v_mov_b32_e32 v73, v2
	v_mov_b32_e32 v74, v2
	v_mov_b32_e32 v75, v2
	v_mov_b32_e32 v76, v2
	v_mov_b32_e32 v77, v2
	v_mov_b32_e32 v86, v2
	v_mov_b32_e32 v87, v2
	v_mov_b32_e32 v88, v2
	v_mov_b32_e32 v89, v2
	v_mov_b32_e32 v90, v2
	v_mov_b32_e32 v91, v2
	v_mov_b32_e32 v92, v2
	v_mov_b32_e32 v93, v2
	v_mov_b32_e32 v102, v2
	v_mov_b32_e32 v103, v2
	v_mov_b32_e32 v104, v2
	v_mov_b32_e32 v105, v2
	v_mov_b32_e32 v106, v2
	v_mov_b32_e32 v107, v2
	v_mov_b32_e32 v108, v2
	v_mov_b32_e32 v109, v2
	v_mov_b32_e32 v118, v2
	v_mov_b32_e32 v119, v2
	v_mov_b32_e32 v120, v2
	v_mov_b32_e32 v121, v2
	v_mov_b32_e32 v122, v2
	v_mov_b32_e32 v123, v2
	v_mov_b32_e32 v124, v2
	v_mov_b32_e32 v125, v2
